# small VALU trims in attention loops (add-zero folds, add3 address forms, dead alpha moves) and NA scalar-base prefetch
# speedup vs baseline: 1.0148x; 1.0037x over previous
; DI f32x16 mfma32(bf16x8 a, bf16x8 b, f32x16 c) { return __builtin_amdgcn_mfma_f32_32x32x16_bf16(a, b, c, 0, 0, 0); }
; DI void attn_diff_unit(const Params& p, int li, int b, int h, int qb, char* smem, bool pre, int nh, bool has_next) {
;     ...
;       const int kbase = kt * 128 + sub * 64;
;       const int relmin = kbase - (qb * 128 + 127), relmax = kbase + 63 - qb * 128;
;       const float cb = (relmin >= 128) ? cR : ((relmax <= -128) ? cL : 0.f);
;       f32x16 s0, s1;
; #pragma unroll
;       for (int i = 0; i < 16; ++i) { s0[i] = cb - m; s1[i] = cb - m; }
;       {
;         bf16x8 kf[8];
; #pragma unroll
;         for (int s = 0; s < 4; ++s) {
;           kf[2 * s] = *(const bf16x8*)(ks + (sub * 64 + r32) * KR + (map * 64 + s * 16 + hh * 8) * 2);
;           kf[2 * s + 1] = *(const bf16x8*)(ks + (sub * 64 + 32 + r32) * KR + (map * 64 + s * 16 + hh * 8) * 2);
;         }
;         __builtin_amdgcn_sched_barrier(0); __builtin_amdgcn_s_setprio(1);
; #pragma unroll
;         for (int s = 0; s < 4; ++s) { s0 = mfma32(kf[2 * s], qf[s], s0); s1 = mfma32(kf[2 * s + 1], qf[s], s1); }
;       __builtin_amdgcn_s_setprio(0);
; }
;       if (relmin < 128 && relmax > -128) {
;         const int base = kbase - qpos + 255 + 4 * hh;
; #pragma unroll
;         for (int i = 0; i < 16; ++i) {
;           int i0 = base + (i & 3) + 8 * (i >> 2);
;           int i1 = i0 + 32;
;           i0 = i0 < 0 ? 0 : (i0 > 510 ? 510 : i0);
;           i1 = i1 < 0 ? 0 : (i1 > 510 ? 510 : i1);
;           s0[i] += tab[i0]; s1[i] += tab[i1];
;         }
;       }
.LBB0_568:
	v_add3_u32 v174, s45, v167, v165
	ds_read_b128 v[176:179], v174
	ds_read_b128 v[224:227], v174 offset:32
	ds_read_b128 v[228:231], v174 offset:8704
	ds_read_b128 v[232:235], v174 offset:8736
	ds_read_b128 v[242:245], v174 offset:64
	ds_read_b128 v[212:215], v174 offset:96
	ds_read_b128 v[216:219], v174 offset:8768
	ds_read_b128 v[220:223], v174 offset:8800
	s_add_i32 s44, s42, s24
	s_cmp_ge_i32 s44, 0xff
	s_cselect_b64 vcc, -1, 0
	s_cmp_le_i32 s44, 0xffffff41
	s_cselect_b64 s[2:3], -1, 0
	v_cndmask_b32_e64 v196, 0, v156, s[2:3]
	v_cndmask_b32_e32 v196, v196, v157, vcc
	v_sub_f32_e32 v196, v196, v169
	v_mov_b32_e32 v197, v196
	v_mov_b64_e32 v[198:199], v[196:197]
	v_mov_b64_e32 v[200:201], v[196:197]
	v_mov_b64_e32 v[202:203], v[196:197]
	v_mov_b64_e32 v[204:205], v[196:197]
	v_mov_b64_e32 v[206:207], v[196:197]
	v_mov_b64_e32 v[208:209], v[196:197]
	v_mov_b64_e32 v[210:211], v[196:197]
	s_nop 0
	s_waitcnt lgkmcnt(4)
	v_mfma_f32_32x32x16_bf16 v[80:95], v[176:179], v[96:99], v[196:211]
	v_mfma_f32_32x32x16_bf16 v[64:79], v[228:231], v[96:99], v[196:211]
	v_mfma_f32_32x32x16_bf16 v[80:95], v[224:227], v[100:103], v[80:95]
	v_mfma_f32_32x32x16_bf16 v[64:79], v[232:235], v[100:103], v[64:79]
	s_waitcnt lgkmcnt(0)
	v_mfma_f32_32x32x16_bf16 v[80:95], v[242:245], v[104:107], v[80:95]
	v_mfma_f32_32x32x16_bf16 v[64:79], v[216:219], v[104:107], v[64:79]
	v_mfma_f32_32x32x16_bf16 v[80:95], v[212:215], v[108:111], v[80:95]
	v_mfma_f32_32x32x16_bf16 v[64:79], v[220:223], v[108:111], v[64:79]
	s_or_b64 s[2:3], s[2:3], vcc
	v_add_u32_e32 v173, s24, v168
	s_and_b64 vcc, exec, s[2:3]
	s_cbranch_vccnz .LBB0_570
	v_add_u32_e32 v177, 0x100, v173
	s_add_i32 s2, 0, 0x25000
	v_med3_i32 v178, v177, 0, v192
	v_med3_i32 v177, v177, s33, v193
	v_lshl_add_u32 v180, v177, 2, s2
	v_add_u32_e32 v177, 0x101, v173
	v_lshl_add_u32 v179, v178, 2, s2
	v_med3_i32 v178, v177, 0, v192
	v_med3_i32 v177, v177, s33, v193
	v_add_u32_e32 v199, 0x108, v173
	v_add_u32_e32 v175, 0xff, v173
	v_lshl_add_u32 v196, v177, 2, s2
	v_add_u32_e32 v177, 0x102, v173
	v_med3_i32 v200, v199, 0, v192
	v_med3_i32 v199, v199, s33, v193
	v_med3_i32 v176, v175, 0, v192
	v_med3_i32 v175, v175, s33, v193
	v_lshl_add_u32 v181, v178, 2, s2
	v_med3_i32 v178, v177, 0, v192
	v_lshl_add_u32 v202, v199, 2, s2
	v_add_u32_e32 v199, 0x109, v173
	v_lshl_add_u32 v176, v176, 2, s2
	v_lshl_add_u32 v175, v175, 2, s2
	v_med3_i32 v177, v177, s33, v193
	v_lshl_add_u32 v197, v178, 2, s2
	v_lshl_add_u32 v201, v200, 2, s2
	v_med3_i32 v200, v199, 0, v192
	v_med3_i32 v199, v199, s33, v193
	v_add_u32_e32 v207, 0x110, v173
	v_lshl_add_u32 v198, v177, 2, s2
	ds_read_b32 v176, v176
	ds_read_b32 v178, v175 offset:128
	ds_read_b32 v177, v179
	ds_read_b32 v179, v180 offset:128
	ds_read_b32 v180, v181
	ds_read_b32 v196, v196 offset:128
	ds_read_b32 v181, v197
	ds_read_b32 v197, v198 offset:128
	v_add_u32_e32 v175, 0x107, v173
	v_lshl_add_u32 v204, v199, 2, s2
	v_add_u32_e32 v199, 0x10a, v173
	v_med3_i32 v208, v207, 0, v192
	v_med3_i32 v207, v207, s33, v193
	v_med3_i32 v198, v175, 0, v192
	v_med3_i32 v175, v175, s33, v193
	v_lshl_add_u32 v203, v200, 2, s2
	v_med3_i32 v200, v199, 0, v192
	v_lshl_add_u32 v210, v207, 2, s2
	v_add_u32_e32 v207, 0x111, v173
	v_lshl_add_u32 v198, v198, 2, s2
	v_lshl_add_u32 v175, v175, 2, s2
	v_med3_i32 v199, v199, s33, v193
	v_lshl_add_u32 v205, v200, 2, s2
	v_lshl_add_u32 v209, v208, 2, s2
	v_med3_i32 v208, v207, 0, v192
	v_med3_i32 v207, v207, s33, v193
	v_add_u32_e32 v215, 0x118, v173
	v_lshl_add_u32 v206, v199, 2, s2
	ds_read_b32 v198, v198
	ds_read_b32 v200, v175 offset:128
	ds_read_b32 v199, v201
	ds_read_b32 v201, v202 offset:128
	ds_read_b32 v202, v203
	ds_read_b32 v204, v204 offset:128
	ds_read_b32 v203, v205
	ds_read_b32 v205, v206 offset:128
	v_add_u32_e32 v175, 0x10f, v173
	v_lshl_add_u32 v212, v207, 2, s2
	v_add_u32_e32 v207, 0x112, v173
	v_med3_i32 v216, v215, 0, v192
	v_med3_i32 v215, v215, s33, v193
	v_med3_i32 v206, v175, 0, v192
	v_med3_i32 v175, v175, s33, v193
	v_lshl_add_u32 v211, v208, 2, s2
	v_med3_i32 v208, v207, 0, v192
	v_lshl_add_u32 v222, v215, 2, s2
	v_add_u32_e32 v215, 0x119, v173
	v_lshl_add_u32 v206, v206, 2, s2
	v_lshl_add_u32 v175, v175, 2, s2
	v_med3_i32 v207, v207, s33, v193
	v_lshl_add_u32 v213, v208, 2, s2
	v_lshl_add_u32 v217, v216, 2, s2
	v_med3_i32 v216, v215, 0, v192
	v_med3_i32 v215, v215, s33, v193
	v_lshl_add_u32 v214, v207, 2, s2
	ds_read_b32 v206, v206
	ds_read_b32 v208, v175 offset:128
	ds_read_b32 v207, v209
	ds_read_b32 v209, v210 offset:128
	ds_read_b32 v210, v211
	ds_read_b32 v212, v212 offset:128
	ds_read_b32 v211, v213
	ds_read_b32 v213, v214 offset:128
	v_add_u32_e32 v175, 0x117, v173
	v_lshl_add_u32 v220, v215, 2, s2
	v_add_u32_e32 v215, 0x11a, v173
	v_med3_i32 v214, v175, 0, v192
	v_lshl_add_u32 v218, v216, 2, s2
	v_med3_i32 v216, v215, 0, v192
	v_med3_i32 v215, v215, s33, v193
	v_med3_i32 v175, v175, s33, v193
	v_lshl_add_u32 v214, v214, 2, s2
	v_lshl_add_u32 v219, v216, 2, s2
	v_lshl_add_u32 v221, v215, 2, s2
	v_lshl_add_u32 v175, v175, 2, s2
	ds_read_b32 v214, v214
	ds_read_b32 v216, v175 offset:128
	ds_read_b32 v218, v218
	ds_read_b32 v219, v219
	ds_read_b32 v215, v217
	ds_read_b32 v221, v221 offset:128
	ds_read_b32 v220, v220 offset:128
	ds_read_b32 v217, v222 offset:128
	s_waitcnt lgkmcnt(4)
	v_pk_add_f32 v[94:95], v[94:95], v[218:219]
	s_waitcnt lgkmcnt(3)
	v_pk_add_f32 v[92:93], v[92:93], v[214:215]
	v_pk_add_f32 v[90:91], v[90:91], v[210:211]
	v_pk_add_f32 v[88:89], v[88:89], v[206:207]
	v_pk_add_f32 v[86:87], v[86:87], v[202:203]
	v_pk_add_f32 v[84:85], v[84:85], v[198:199]
	v_pk_add_f32 v[82:83], v[82:83], v[180:181]
	v_pk_add_f32 v[80:81], v[80:81], v[176:177]
	s_waitcnt lgkmcnt(1)
	v_pk_add_f32 v[78:79], v[78:79], v[220:221]
	s_waitcnt lgkmcnt(0)
	v_pk_add_f32 v[76:77], v[76:77], v[216:217]
	v_pk_add_f32 v[74:75], v[74:75], v[212:213]
	v_pk_add_f32 v[72:73], v[72:73], v[208:209]
	v_pk_add_f32 v[70:71], v[70:71], v[204:205]
	v_pk_add_f32 v[68:69], v[68:69], v[200:201]
	v_pk_add_f32 v[66:67], v[66:67], v[196:197]
	v_pk_add_f32 v[64:65], v[64:65], v[178:179]

; DI bool softmax_tile(f32x16& s0, f32x16& s1, float& m, float& l, float& alpha, bf16x8* pf, int lane, bool first, bool check) {
;   if (first) {
;     float mx = fmaxf(s0[0], s1[0]);
; #pragma unroll
;     for (int i = 1; i < 16; ++i) mx = fmaxf(mx, fmaxf(s0[i], s1[i]));
;     mx = fmaxf(mx, shx(mx, 32, lane));
;     m += mx;
; #pragma unroll
;     for (int i = 0; i < 16; ++i) { s0[i] -= mx; s1[i] -= mx; }
;   }
;   float sum = 0.f;
; #pragma unroll
;   for (int i = 0; i < 16; ++i) { s0[i] = __builtin_amdgcn_exp2f(s0[i]); sum += s0[i]; }
; #pragma unroll
;   for (int i = 0; i < 16; ++i) { s1[i] = __builtin_amdgcn_exp2f(s1[i]); sum += s1[i]; }
;   l += sum;
;   pf[0] = pack8(s0, 0); pf[1] = pack8(s0, 8); pf[2] = pack8(s1, 0); pf[3] = pack8(s1, 8);
;   alpha = 1.f;
;   if (!check) return false;
;   const float rsum = sum + shx(sum, 32, lane);
;   const bool trig = rsum > 65536.f;
;   const bool resc = (__builtin_amdgcn_ballot_w64(trig) != 0ull);
;   alpha = 1.f;
;   if (resc) {
;     const float d = trig ? (float)(__builtin_amdgcn_frexp_expf(rsum) - 7) : 0.f;
;     alpha = __builtin_amdgcn_exp2f(-d);
;     m += d; l *= alpha;
;   }
.LBB0_572:
	v_add3_u32 v175, s45, v164, v163
	ds_read_b128 v[212:215], v174 offset:17408
	ds_read_b128 v[216:219], v174 offset:26112
	ds_read_b128 v[220:223], v174 offset:17440
	ds_read_b128 v[224:227], v174 offset:26144
	ds_read_b128 v[228:231], v174 offset:17472
	ds_read_b128 v[232:235], v174 offset:26176
	ds_read_b128 v[176:179], v174 offset:17504
	ds_read_b128 v[242:245], v174 offset:26208
	v_add_u32_e32 v236, 0x8800, v175
	v_exp_f32_e32 v80, v80
	v_exp_f32_e32 v81, v81
	v_exp_f32_e32 v82, v82
	v_exp_f32_e32 v83, v83
	v_exp_f32_e32 v84, v84
	v_add_f32_e32 v250, v81, v80
	v_exp_f32_e32 v85, v85
	v_add_f32_e32 v250, v82, v250
	v_exp_f32_e32 v86, v86
	v_add_f32_e32 v250, v83, v250
	v_exp_f32_e32 v87, v87
	v_add_f32_e32 v250, v84, v250
	v_exp_f32_e32 v88, v88
	v_add_f32_e32 v250, v85, v250
	v_exp_f32_e32 v89, v89
	v_add_f32_e32 v250, v86, v250
	v_exp_f32_e32 v90, v90
	v_add_f32_e32 v250, v87, v250
	v_exp_f32_e32 v91, v91
	v_add_f32_e32 v250, v88, v250
	v_exp_f32_e32 v92, v92
	v_add_f32_e32 v250, v89, v250
	v_exp_f32_e32 v93, v93
	v_add_f32_e32 v250, v90, v250
	v_exp_f32_e32 v94, v94
	v_add_f32_e32 v250, v91, v250
	v_exp_f32_e32 v95, v95
	v_add_f32_e32 v250, v92, v250
	v_exp_f32_e32 v64, v64
	v_add_f32_e32 v250, v93, v250
	v_exp_f32_e32 v65, v65
	v_add_f32_e32 v250, v94, v250
	v_exp_f32_e32 v66, v66
	v_add_f32_e32 v250, v95, v250
	v_exp_f32_e32 v67, v67
	v_add_f32_e32 v250, v64, v250
	v_exp_f32_e32 v68, v68
	v_add_f32_e32 v250, v65, v250
	v_exp_f32_e32 v69, v69
	v_add_f32_e32 v250, v66, v250
	v_exp_f32_e32 v70, v70
	v_add_f32_e32 v250, v67, v250
	v_exp_f32_e32 v71, v71
	v_add_f32_e32 v250, v68, v250
	v_exp_f32_e32 v72, v72
	v_add_f32_e32 v250, v69, v250
	v_exp_f32_e32 v73, v73
	v_add_f32_e32 v250, v70, v250
	v_exp_f32_e32 v74, v74
	v_add_f32_e32 v250, v71, v250
	v_exp_f32_e32 v75, v75
	v_add_f32_e32 v250, v72, v250
	v_exp_f32_e32 v76, v76
	v_add_f32_e32 v250, v73, v250
	v_exp_f32_e32 v77, v77
	v_add_f32_e32 v250, v74, v250
	v_exp_f32_e32 v78, v78
	v_add_f32_e32 v250, v75, v250
	v_exp_f32_e32 v79, v79
	v_add_f32_e32 v250, v76, v250
	v_add_f32_e32 v250, v77, v250
	v_add_f32_e32 v250, v78, v250
	v_add_f32_e32 v250, v79, v250
	s_and_b32 s2, s43, 3
	v_add_f32_e32 v172, v172, v250
	s_mov_b64 s[100:101], 0
	s_cmp_lg_u32 s2, 0
	s_cbranch_scc1 .Ldp_ck_done
	ds_bpermute_b32 v251, v147, v250
	s_waitcnt lgkmcnt(0)
	v_add_f32_e32 v250, v250, v251
	v_cmp_lt_f32_e32 vcc, s88, v250
	s_cbranch_vccz .Ldp_ck_done
	v_frexp_exp_i32_f32_e32 v251, v250
	v_add_u32_e32 v251, -7, v251
	v_cvt_f32_i32_e32 v251, v251
	s_mov_b64 s[100:101], -1
	v_cndmask_b32_e32 v251, 0, v251, vcc
	v_exp_f32_e64 v252, -v251
	v_add_f32_e32 v169, v169, v251
	v_mul_f32_e32 v172, v172, v252

; DI f32x16 mfma32(bf16x8 a, bf16x8 b, f32x16 c) { return __builtin_amdgcn_mfma_f32_32x32x16_bf16(a, b, c, 0, 0, 0); }
; DI bool softmax_tile(f32x16& s0, f32x16& s1, float& m, float& l, float& alpha, bf16x8* pf, int lane, bool first, bool check) {
;     ...
;   float sum = 0.f;
; #pragma unroll
;   for (int i = 0; i < 16; ++i) { s0[i] = __builtin_amdgcn_exp2f(s0[i]); sum += s0[i]; }
; #pragma unroll
;   for (int i = 0; i < 16; ++i) { s1[i] = __builtin_amdgcn_exp2f(s1[i]); sum += s1[i]; }
;   l += sum;
;   pf[0] = pack8(s0, 0); pf[1] = pack8(s0, 8); pf[2] = pack8(s1, 0); pf[3] = pack8(s1, 8);
; DI void attn_diff_unit(const Params& p, int li, int b, int h, int qb, char* smem, bool pre, int nh, bool has_next) {
;     ...
;       {
;         bf16x8 vf[2][4];
; #pragma unroll
;         for (int j = 0; j < 4; ++j) vf[0][j] = ld_vfrag_tr(vs, vbase, VR, sub * 64, j * 32);
; #pragma unroll
;         for (int s = 0; s < 4; ++s) {
;           if (s < 3) {
; #pragma unroll
;             for (int j = 0; j < 4; ++j) vf[(s + 1) & 1][j] = ld_vfrag_tr(vs, vbase, VR, sub * 64 + 16 * (s + 1), j * 32);
;           }
;           __builtin_amdgcn_sched_barrier(0); __builtin_amdgcn_s_setprio(1);
; #pragma unroll
;           for (int j = 0; j < 4; ++j) O[j] = mfma32(vf[s & 1][j], pf[s], O[j]);
;         __builtin_amdgcn_s_setprio(0);
; }
;       }
.Ldp_b1_skip:
	ds_read_b64_tr_b16 v[212:213], v175 offset:34816
	ds_read_b64_tr_b16 v[214:215], v175 offset:37376
	ds_read_b64_tr_b16 v[216:217], v175 offset:34880
	ds_read_b64_tr_b16 v[218:219], v175 offset:37440
	ds_read_b64_tr_b16 v[220:221], v175 offset:34944
	ds_read_b64_tr_b16 v[222:223], v175 offset:37504
	ds_read_b64_tr_b16 v[224:225], v175 offset:35008
	ds_read_b64_tr_b16 v[226:227], v175 offset:37568
	ds_read_b64_tr_b16 v[228:229], v175 offset:39936
	ds_read_b64_tr_b16 v[230:231], v175 offset:42496
	ds_read_b64_tr_b16 v[232:233], v175 offset:40000
	ds_read_b64_tr_b16 v[234:235], v175 offset:42560
	ds_read_b64_tr_b16 v[176:177], v175 offset:40064
	ds_read_b64_tr_b16 v[178:179], v175 offset:42624
	ds_read_b64_tr_b16 v[242:243], v175 offset:40128
	ds_read_b64_tr_b16 v[244:245], v175 offset:42688
	s_waitcnt lgkmcnt(8)
	v_mfma_f32_32x32x16_bf16 v[48:63], v[212:215], v[72:75], v[48:63]
	v_exp_f32_e32 v80, v80
	v_exp_f32_e32 v81, v81
	v_mfma_f32_32x32x16_bf16 v[32:47], v[216:219], v[72:75], v[32:47]
	v_exp_f32_e32 v82, v82
	v_exp_f32_e32 v83, v83
	v_add_f32_e32 v253, v81, v80
	v_mfma_f32_32x32x16_bf16 v[16:31], v[220:223], v[72:75], v[16:31]
	v_exp_f32_e32 v84, v84
	v_exp_f32_e32 v85, v85
	v_add_f32_e32 v253, v82, v253
	v_add_f32_e32 v253, v83, v253
	v_mfma_f32_32x32x16_bf16 v[0:15], v[224:227], v[72:75], v[0:15]
	v_exp_f32_e32 v86, v86
	v_exp_f32_e32 v87, v87
	v_add_f32_e32 v253, v84, v253
	v_add_f32_e32 v253, v85, v253
	ds_read_b64_tr_b16 v[212:213], v175 offset:45056
	ds_read_b64_tr_b16 v[214:215], v175 offset:47616
	ds_read_b64_tr_b16 v[216:217], v175 offset:45120
	ds_read_b64_tr_b16 v[218:219], v175 offset:47680
	ds_read_b64_tr_b16 v[220:221], v175 offset:45184
	ds_read_b64_tr_b16 v[222:223], v175 offset:47744
	ds_read_b64_tr_b16 v[224:225], v175 offset:45248
	ds_read_b64_tr_b16 v[226:227], v175 offset:47808
	s_waitcnt lgkmcnt(8)
	v_mfma_f32_32x32x16_bf16 v[48:63], v[228:231], v[76:79], v[48:63]
	v_exp_f32_e32 v88, v88
	v_exp_f32_e32 v89, v89
	v_add_f32_e32 v253, v86, v253
	v_add_f32_e32 v253, v87, v253
	v_cvt_pk_bf16_f32 v80, v80, v81
	v_mfma_f32_32x32x16_bf16 v[32:47], v[232:235], v[76:79], v[32:47]
	v_exp_f32_e32 v90, v90
	v_exp_f32_e32 v91, v91
	v_add_f32_e32 v253, v88, v253
	v_add_f32_e32 v253, v89, v253
	v_cvt_pk_bf16_f32 v81, v82, v83
	v_mfma_f32_32x32x16_bf16 v[16:31], v[176:179], v[76:79], v[16:31]
	v_exp_f32_e32 v92, v92
	v_exp_f32_e32 v93, v93
	v_add_f32_e32 v253, v90, v253
	v_add_f32_e32 v253, v91, v253
	v_cvt_pk_bf16_f32 v82, v84, v85
	v_mfma_f32_32x32x16_bf16 v[0:15], v[242:245], v[76:79], v[0:15]
	v_exp_f32_e32 v94, v94
	v_exp_f32_e32 v95, v95
	v_add_f32_e32 v253, v92, v253
	v_add_f32_e32 v253, v93, v253
	v_cvt_pk_bf16_f32 v83, v86, v87
	ds_read_b64_tr_b16 v[228:229], v175 offset:50176
	ds_read_b64_tr_b16 v[230:231], v175 offset:52736
	ds_read_b64_tr_b16 v[232:233], v175 offset:50240
	ds_read_b64_tr_b16 v[234:235], v175 offset:52800
	ds_read_b64_tr_b16 v[176:177], v175 offset:50304
	ds_read_b64_tr_b16 v[178:179], v175 offset:52864
	ds_read_b64_tr_b16 v[242:243], v175 offset:50368
	ds_read_b64_tr_b16 v[244:245], v175 offset:52928
	s_waitcnt lgkmcnt(8)
	v_mfma_f32_32x32x16_bf16 v[48:63], v[212:215], v[64:67], v[48:63]
	v_exp_f32_e32 v196, v196
	v_exp_f32_e32 v197, v197
	v_add_f32_e32 v253, v94, v253
	v_add_f32_e32 v253, v95, v253
	v_cvt_pk_bf16_f32 v84, v88, v89
	v_mfma_f32_32x32x16_bf16 v[32:47], v[216:219], v[64:67], v[32:47]
	v_exp_f32_e32 v198, v198
	v_exp_f32_e32 v199, v199
	v_add_f32_e32 v253, v196, v253
	v_add_f32_e32 v253, v197, v253
	v_cvt_pk_bf16_f32 v85, v90, v91
	v_mfma_f32_32x32x16_bf16 v[16:31], v[220:223], v[64:67], v[16:31]
	v_exp_f32_e32 v200, v200
	v_exp_f32_e32 v201, v201
	v_add_f32_e32 v253, v198, v253
	v_add_f32_e32 v253, v199, v253
	v_cvt_pk_bf16_f32 v86, v92, v93
	v_mfma_f32_32x32x16_bf16 v[0:15], v[224:227], v[64:67], v[0:15]
	v_exp_f32_e32 v202, v202
	v_exp_f32_e32 v203, v203
	v_add_f32_e32 v253, v200, v253
	v_add_f32_e32 v253, v201, v253
	v_cvt_pk_bf16_f32 v87, v94, v95
	s_waitcnt lgkmcnt(0)
	v_mfma_f32_32x32x16_bf16 v[48:63], v[228:231], v[68:71], v[48:63]
	v_exp_f32_e32 v204, v204
	v_exp_f32_e32 v205, v205
	v_add_f32_e32 v253, v202, v253
	v_add_f32_e32 v253, v203, v253
	v_cvt_pk_bf16_f32 v196, v196, v197
	v_mfma_f32_32x32x16_bf16 v[32:47], v[232:235], v[68:71], v[32:47]
	v_exp_f32_e32 v206, v206
	v_exp_f32_e32 v207, v207
	v_add_f32_e32 v253, v204, v253
	v_add_f32_e32 v253, v205, v253
	v_cvt_pk_bf16_f32 v197, v198, v199
	v_mfma_f32_32x32x16_bf16 v[16:31], v[176:179], v[68:71], v[16:31]
	v_exp_f32_e32 v208, v208
	v_exp_f32_e32 v209, v209
	v_add_f32_e32 v253, v206, v253
	v_add_f32_e32 v253, v207, v253
	v_cvt_pk_bf16_f32 v198, v200, v201
	v_mfma_f32_32x32x16_bf16 v[0:15], v[242:245], v[68:71], v[0:15]
	v_exp_f32_e32 v210, v210
	v_exp_f32_e32 v211, v211
	v_add_f32_e32 v253, v208, v253
	v_add_f32_e32 v253, v209, v253
	v_cvt_pk_bf16_f32 v199, v202, v203
	v_add_f32_e32 v253, v210, v253
	v_add_f32_e32 v253, v211, v253
	v_cvt_pk_bf16_f32 v200, v204, v205
	v_cvt_pk_bf16_f32 v201, v206, v207
	v_cvt_pk_bf16_f32 v202, v208, v209
	v_cvt_pk_bf16_f32 v203, v210, v211
	v_add_f32_e32 v172, v172, v253
	s_andn2_b64 vcc, exec, s[100:101]
	s_cbranch_vccnz .Ldp_nors
; DI void attn_diff_unit(const Params& p, int li, int b, int h, int qb, char* smem, bool pre, int nh, bool has_next) {
;     ...
;       if (resc) {
; #pragma unroll
;         for (int j = 0; j < 4; ++j) scale16(O[j], alpha);
;       }
	s_nop 15
	v_mul_f32_e32 v0, v0, v252
	v_mul_f32_e32 v1, v1, v252
	v_mul_f32_e32 v2, v2, v252
	v_mul_f32_e32 v3, v3, v252
	v_mul_f32_e32 v4, v4, v252
	v_mul_f32_e32 v5, v5, v252
	v_mul_f32_e32 v6, v6, v252
	v_mul_f32_e32 v7, v7, v252
	v_mul_f32_e32 v8, v8, v252
	v_mul_f32_e32 v9, v9, v252
	v_mul_f32_e32 v10, v10, v252
	v_mul_f32_e32 v11, v11, v252
	v_mul_f32_e32 v12, v12, v252
	v_mul_f32_e32 v13, v13, v252
	v_mul_f32_e32 v14, v14, v252
	v_mul_f32_e32 v15, v15, v252
	v_mul_f32_e32 v16, v16, v252
	v_mul_f32_e32 v17, v17, v252
	v_mul_f32_e32 v18, v18, v252
	v_mul_f32_e32 v19, v19, v252
	v_mul_f32_e32 v20, v20, v252
	v_mul_f32_e32 v21, v21, v252
	v_mul_f32_e32 v22, v22, v252
	v_mul_f32_e32 v23, v23, v252
	v_mul_f32_e32 v24, v24, v252
	v_mul_f32_e32 v25, v25, v252
	v_mul_f32_e32 v26, v26, v252
	v_mul_f32_e32 v27, v27, v252
	v_mul_f32_e32 v28, v28, v252
	v_mul_f32_e32 v29, v29, v252
	v_mul_f32_e32 v30, v30, v252
	v_mul_f32_e32 v31, v31, v252
	v_mul_f32_e32 v32, v32, v252
	v_mul_f32_e32 v33, v33, v252
	v_mul_f32_e32 v34, v34, v252
	v_mul_f32_e32 v35, v35, v252
	v_mul_f32_e32 v36, v36, v252
	v_mul_f32_e32 v37, v37, v252
	v_mul_f32_e32 v38, v38, v252
	v_mul_f32_e32 v39, v39, v252
	v_mul_f32_e32 v40, v40, v252
	v_mul_f32_e32 v41, v41, v252
	v_mul_f32_e32 v42, v42, v252
	v_mul_f32_e32 v43, v43, v252
	v_mul_f32_e32 v44, v44, v252
	v_mul_f32_e32 v45, v45, v252
	v_mul_f32_e32 v46, v46, v252
	v_mul_f32_e32 v47, v47, v252
	v_mul_f32_e32 v48, v48, v252
	v_mul_f32_e32 v49, v49, v252
	v_mul_f32_e32 v50, v50, v252
	v_mul_f32_e32 v51, v51, v252
	v_mul_f32_e32 v52, v52, v252
	v_mul_f32_e32 v53, v53, v252
	v_mul_f32_e32 v54, v54, v252
	v_mul_f32_e32 v55, v55, v252
	v_mul_f32_e32 v56, v56, v252
	v_mul_f32_e32 v57, v57, v252
	v_mul_f32_e32 v58, v58, v252
	v_mul_f32_e32 v59, v59, v252
	v_mul_f32_e32 v60, v60, v252
	v_mul_f32_e32 v61, v61, v252
	v_mul_f32_e32 v62, v62, v252
	v_mul_f32_e32 v63, v63, v252

; DI f32x16 mfma32(bf16x8 a, bf16x8 b, f32x16 c) { return __builtin_amdgcn_mfma_f32_32x32x16_bf16(a, b, c, 0, 0, 0); }
; DI bool softmax_tile(f32x16& s0, f32x16& s1, float& m, float& l, float& alpha, bf16x8* pf, int lane, bool first, bool check) {
;     ...
;   float sum = 0.f;
; #pragma unroll
;   for (int i = 0; i < 16; ++i) { s0[i] = __builtin_amdgcn_exp2f(s0[i]); sum += s0[i]; }
; #pragma unroll
;   for (int i = 0; i < 16; ++i) { s1[i] = __builtin_amdgcn_exp2f(s1[i]); sum += s1[i]; }
;   l += sum;
;   pf[0] = pack8(s0, 0); pf[1] = pack8(s0, 8); pf[2] = pack8(s1, 0); pf[3] = pack8(s1, 8);
;   alpha = 1.f;
;   if (!check) return false;
; DI void attn_mla_unit(const Params& p, int b, int h, int qb, char* smem, bool pre, int nh, bool has_next) {
;     ...
;       {
;         bf16x8 kf[12];
; #pragma unroll
;         for (int s = 0; s < 6; ++s) {
;           kf[2 * s] = *(const bf16x8*)(ks + (sub * 64 + r32) * KR + (s * 16 + hh * 8) * 2);
;           kf[2 * s + 1] = *(const bf16x8*)(ks + (sub * 64 + 32 + r32) * KR + (s * 16 + hh * 8) * 2);
;         }
;         __builtin_amdgcn_sched_barrier(0); __builtin_amdgcn_s_setprio(1);
; #pragma unroll
;         for (int s = 0; s < 6; ++s) { s0 = mfma32(kf[2 * s], qf[s], s0); s1 = mfma32(kf[2 * s + 1], qf[s], s1); }
;       __builtin_amdgcn_s_setprio(0);
; }
;       float alpha; bf16x8 pf[4];
;       const bool resc = softmax_tile(s0, s1, m, l, alpha, pf, lane, (kt == 0) && (sub == 0), (sub == 0) && ((kt & 3) == 0));
.LBB0_1482:
	s_add_i32 s19, s18, -1
	s_bitcmp1_b32 s19, 0
	s_cselect_b32 s16, 0xc800, 0
	s_add_i32 s20, s16, 0
	v_add3_u32 v67, s20, v149, v144
	ds_read_b128 v[68:71], v67
	ds_read_b128 v[72:75], v67 offset:32
	ds_read_b128 v[76:79], v67 offset:6656
	ds_read_b128 v[132:135], v67 offset:6688
	ds_read_b128 v[154:157], v67 offset:64
	ds_read_b128 v[158:161], v67 offset:96
	ds_read_b128 v[162:165], v67 offset:6720
	ds_read_b128 v[166:169], v67 offset:6752
	ds_read_b128 v[170:173], v67 offset:128
	ds_read_b128 v[174:177], v67 offset:160
	ds_read_b128 v[178:181], v67 offset:6784
	ds_read_b128 v[196:199], v67 offset:6816
	s_and_b32 s16, s19, 3
	s_setprio 1
	s_waitcnt lgkmcnt(8)
	v_mfma_f32_32x32x16_bf16 v[48:63], v[68:71], v[100:103], v[220:235]
	v_mfma_f32_32x32x16_bf16 v[32:47], v[76:79], v[100:103], v[220:235]
	v_mfma_f32_32x32x16_bf16 v[48:63], v[72:75], v[96:99], v[48:63]
	v_mfma_f32_32x32x16_bf16 v[32:47], v[132:135], v[96:99], v[32:47]
	s_waitcnt lgkmcnt(4)
	v_mfma_f32_32x32x16_bf16 v[48:63], v[154:157], v[92:95], v[48:63]
	v_mfma_f32_32x32x16_bf16 v[32:47], v[162:165], v[92:95], v[32:47]
	v_mfma_f32_32x32x16_bf16 v[48:63], v[158:161], v[88:91], v[48:63]
	v_mfma_f32_32x32x16_bf16 v[32:47], v[166:169], v[88:91], v[32:47]
	s_waitcnt lgkmcnt(0)
	v_mfma_f32_32x32x16_bf16 v[48:63], v[170:173], v[84:87], v[48:63]
	v_mfma_f32_32x32x16_bf16 v[32:47], v[178:181], v[84:87], v[32:47]
	v_mfma_f32_32x32x16_bf16 v[48:63], v[174:177], v[80:83], v[48:63]
	v_mfma_f32_32x32x16_bf16 v[32:47], v[196:199], v[80:83], v[32:47]
	s_setprio 0
	s_nop 9
	v_exp_f32_e32 v48, v48
	v_exp_f32_e32 v49, v49
	v_exp_f32_e32 v50, v50
	v_exp_f32_e32 v51, v51
	v_exp_f32_e32 v52, v52
	v_add_f32_e32 v66, v49, v48
	v_exp_f32_e32 v53, v53
	v_add_f32_e32 v66, v50, v66
	v_exp_f32_e32 v54, v54
	v_add_f32_e32 v66, v51, v66
	v_exp_f32_e32 v55, v55
	v_add_f32_e32 v66, v52, v66
	v_exp_f32_e32 v56, v56
	v_add_f32_e32 v66, v53, v66
	v_exp_f32_e32 v57, v57
	v_add_f32_e32 v66, v54, v66
	v_exp_f32_e32 v58, v58
	v_add_f32_e32 v66, v55, v66
	v_exp_f32_e32 v59, v59
	v_add_f32_e32 v66, v56, v66
	v_exp_f32_e32 v60, v60
	v_add_f32_e32 v66, v57, v66
	v_exp_f32_e32 v61, v61
	v_add_f32_e32 v66, v58, v66
	v_exp_f32_e32 v62, v62
	v_add_f32_e32 v66, v59, v66
	v_exp_f32_e32 v63, v63
	v_add_f32_e32 v66, v60, v66
	v_exp_f32_e32 v68, v32
	v_add_f32_e32 v66, v61, v66
	v_exp_f32_e32 v33, v33
	v_add_f32_e32 v66, v62, v66
	v_exp_f32_e32 v34, v34
	v_add_f32_e32 v66, v63, v66
	v_exp_f32_e32 v35, v35
	v_add_f32_e32 v32, v68, v66
	v_exp_f32_e32 v36, v36
	v_add_f32_e32 v32, v33, v32
	v_exp_f32_e32 v37, v37
	v_add_f32_e32 v32, v34, v32
	v_exp_f32_e32 v38, v38
	v_add_f32_e32 v32, v35, v32
	v_exp_f32_e32 v39, v39
	v_add_f32_e32 v32, v36, v32
	v_exp_f32_e32 v40, v40
	v_add_f32_e32 v32, v37, v32
	v_exp_f32_e32 v41, v41
	v_add_f32_e32 v32, v38, v32
	v_exp_f32_e32 v42, v42
	v_add_f32_e32 v32, v39, v32
	v_exp_f32_e32 v43, v43
	v_add_f32_e32 v32, v40, v32
	v_exp_f32_e32 v44, v44
	v_add_f32_e32 v32, v41, v32
	v_exp_f32_e32 v45, v45
	v_add_f32_e32 v32, v42, v32
	v_exp_f32_e32 v46, v46
	v_add_f32_e32 v32, v43, v32
	v_exp_f32_e32 v47, v47
	v_add_f32_e32 v32, v44, v32
	v_add_f32_e32 v32, v45, v32
	v_add_f32_e32 v32, v46, v32
	v_add_f32_e32 v32, v47, v32
	s_cmp_lg_u32 s16, 0
	v_add_f32_e32 v66, v153, v32
	s_cbranch_scc0 .LBB0_1484
	s_mov_b64 s[16:17], 0
	s_branch .LBB0_1487
; DI f32x16 mfma32(bf16x8 a, bf16x8 b, f32x16 c) { return __builtin_amdgcn_mfma_f32_32x32x16_bf16(a, b, c, 0, 0, 0); }
; DI bool softmax_tile(f32x16& s0, f32x16& s1, float& m, float& l, float& alpha, bf16x8* pf, int lane, bool first, bool check) {
;     ...
;   if (!check) return false;
;   const float rsum = sum + shx(sum, 32, lane);
;   const bool trig = rsum > 65536.f;
;   const bool resc = (__builtin_amdgcn_ballot_w64(trig) != 0ull);
;   alpha = 1.f;
;   if (resc) {
;     const float d = trig ? (float)(__builtin_amdgcn_frexp_expf(rsum) - 7) : 0.f;
;     alpha = __builtin_amdgcn_exp2f(-d);
;     m += d; l *= alpha;
;   }
;   return resc;
; DI void attn_mla_unit(const Params& p, int b, int h, int qb, char* smem, bool pre, int nh, bool has_next) {
;     ...
;       float alpha; bf16x8 pf[4];
;       const bool resc = softmax_tile(s0, s1, m, l, alpha, pf, lane, (kt == 0) && (sub == 0), (sub == 0) && ((kt & 3) == 0));
;       {
;         bf16x8 vf[8];
; #pragma unroll
;         for (int s = 0; s < 4; ++s) { vf[2 * s] = ld_vfrag_tr(vs, vbase, VR, sub * 64 + 16 * s, 0); vf[2 * s + 1] = ld_vfrag_tr(vs, vbase, VR, sub * 64 + 16 * s, 32); }
;         __builtin_amdgcn_sched_barrier(0); __builtin_amdgcn_s_setprio(1);
; #pragma unroll
;         for (int s = 0; s < 4; ++s) { O0 = mfma32(vf[2 * s], pf[s], O0); O1 = mfma32(vf[2 * s + 1], pf[s], O1); }
;       __builtin_amdgcn_s_setprio(0);
; }
;       if (resc) { scale16(O0, alpha); scale16(O1, alpha); }
.LBB0_1484:
	ds_bpermute_b32 v69, v140, v32
	s_waitcnt lgkmcnt(0)
	v_add_f32_e32 v32, v32, v69
	v_cmp_lt_f32_e32 vcc, s88, v32
	s_cbranch_vccz .LBB0_1486
	v_frexp_exp_i32_f32_e32 v32, v32
	v_add_u32_e32 v32, -7, v32
	v_cvt_f32_i32_e32 v32, v32
	s_mov_b64 s[16:17], -1
	v_cndmask_b32_e32 v69, 0, v32, vcc
	v_exp_f32_e64 v32, -v69
	v_add_f32_e32 v150, v150, v69
	v_sub_f32_e32 v220, v220, v69
	v_sub_f32_e32 v221, v221, v69
	v_sub_f32_e32 v222, v222, v69
	v_sub_f32_e32 v223, v223, v69
	v_sub_f32_e32 v224, v224, v69
	v_sub_f32_e32 v225, v225, v69
	v_sub_f32_e32 v226, v226, v69
	v_sub_f32_e32 v227, v227, v69
	v_sub_f32_e32 v228, v228, v69
	v_sub_f32_e32 v229, v229, v69
	v_sub_f32_e32 v230, v230, v69
	v_sub_f32_e32 v231, v231, v69
	v_sub_f32_e32 v232, v232, v69
	v_sub_f32_e32 v233, v233, v69
	v_sub_f32_e32 v234, v234, v69
	v_sub_f32_e32 v235, v235, v69
	v_mul_f32_e32 v66, v66, v32
	s_branch .LBB0_1487
.LBB0_1486:
	s_mov_b64 s[16:17], 0
.LBB0_1487:
	v_cvt_pk_bf16_f32 v48, v48, v49
	v_cvt_pk_bf16_f32 v49, v50, v51
	v_cvt_pk_bf16_f32 v50, v52, v53
	v_cvt_pk_bf16_f32 v52, v56, v57
	v_cvt_pk_bf16_f32 v56, v68, v33
	v_add3_u32 v68, s20, v148, v147
	v_cvt_pk_bf16_f32 v51, v54, v55
	v_cvt_pk_bf16_f32 v53, v58, v59
	v_cvt_pk_bf16_f32 v54, v60, v61
	v_cvt_pk_bf16_f32 v55, v62, v63
	v_cvt_pk_bf16_f32 v57, v34, v35
	v_cvt_pk_bf16_f32 v58, v36, v37
	v_cvt_pk_bf16_f32 v59, v38, v39
	v_cvt_pk_bf16_f32 v34, v40, v41
	v_cvt_pk_bf16_f32 v35, v42, v43
	v_cvt_pk_bf16_f32 v36, v44, v45
	ds_read_b64_tr_b16 v[38:39], v68 offset:26624
	ds_read_b64_tr_b16 v[40:41], v68 offset:28160
	ds_read_b64_tr_b16 v[42:43], v68 offset:26688
	ds_read_b64_tr_b16 v[44:45], v68 offset:28224
	ds_read_b64_tr_b16 v[60:61], v68 offset:29696
	ds_read_b64_tr_b16 v[62:63], v68 offset:31232
	ds_read_b64_tr_b16 v[70:71], v68 offset:29760
	ds_read_b64_tr_b16 v[72:73], v68 offset:31296
	ds_read_b64_tr_b16 v[74:75], v68 offset:32768
	ds_read_b64_tr_b16 v[76:77], v68 offset:34304
	ds_read_b64_tr_b16 v[132:133], v68 offset:32832
	ds_read_b64_tr_b16 v[134:135], v68 offset:34368
	ds_read_b64_tr_b16 v[154:155], v68 offset:35840
	ds_read_b64_tr_b16 v[156:157], v68 offset:37376
	ds_read_b64_tr_b16 v[158:159], v68 offset:35904
	ds_read_b64_tr_b16 v[160:161], v68 offset:37440
	v_cvt_pk_bf16_f32 v37, v46, v47
	s_setprio 1
	s_waitcnt lgkmcnt(8)
	v_mfma_f32_32x32x16_bf16 v[16:31], v[38:41], v[48:51], v[16:31]
	v_mfma_f32_32x32x16_bf16 v[0:15], v[42:45], v[48:51], v[0:15]
	v_mfma_f32_32x32x16_bf16 v[16:31], v[60:63], v[52:55], v[16:31]
	v_mfma_f32_32x32x16_bf16 v[0:15], v[70:73], v[52:55], v[0:15]
	s_waitcnt lgkmcnt(0)
	v_mfma_f32_32x32x16_bf16 v[16:31], v[74:77], v[56:59], v[16:31]
	v_mfma_f32_32x32x16_bf16 v[0:15], v[132:135], v[56:59], v[0:15]
	v_mfma_f32_32x32x16_bf16 v[16:31], v[154:157], v[34:37], v[16:31]
	v_mfma_f32_32x32x16_bf16 v[0:15], v[158:161], v[34:37], v[0:15]
	s_setprio 0
	s_andn2_b64 vcc, exec, s[16:17]
	s_cbranch_vccnz .LBB0_1489
	s_nop 7
	v_pk_mul_f32 v[30:31], v[32:33], v[30:31] op_sel_hi:[0,1]
	v_pk_mul_f32 v[28:29], v[32:33], v[28:29] op_sel_hi:[0,1]
	v_pk_mul_f32 v[26:27], v[32:33], v[26:27] op_sel_hi:[0,1]
	v_pk_mul_f32 v[24:25], v[32:33], v[24:25] op_sel_hi:[0,1]
	v_pk_mul_f32 v[22:23], v[32:33], v[22:23] op_sel_hi:[0,1]
	v_pk_mul_f32 v[20:21], v[32:33], v[20:21] op_sel_hi:[0,1]
	v_pk_mul_f32 v[18:19], v[32:33], v[18:19] op_sel_hi:[0,1]
	v_pk_mul_f32 v[16:17], v[32:33], v[16:17] op_sel_hi:[0,1]
	v_pk_mul_f32 v[14:15], v[32:33], v[14:15] op_sel_hi:[0,1]
	v_pk_mul_f32 v[12:13], v[32:33], v[12:13] op_sel_hi:[0,1]
	v_pk_mul_f32 v[10:11], v[32:33], v[10:11] op_sel_hi:[0,1]
	v_pk_mul_f32 v[8:9], v[32:33], v[8:9] op_sel_hi:[0,1]
	v_pk_mul_f32 v[6:7], v[32:33], v[6:7] op_sel_hi:[0,1]
	v_pk_mul_f32 v[4:5], v[32:33], v[4:5] op_sel_hi:[0,1]
	v_pk_mul_f32 v[2:3], v[32:33], v[2:3] op_sel_hi:[0,1]
	v_pk_mul_f32 v[0:1], v[32:33], v[0:1] op_sel_hi:[0,1]

; DI bool softmax_tile(f32x16& s0, f32x16& s1, float& m, float& l, float& alpha, bf16x8* pf, int lane, bool first, bool check) {
;     ...
;   float sum = 0.f;
; #pragma unroll
;   for (int i = 0; i < 16; ++i) { s0[i] = __builtin_amdgcn_exp2f(s0[i]); sum += s0[i]; }
; #pragma unroll
;   for (int i = 0; i < 16; ++i) { s1[i] = __builtin_amdgcn_exp2f(s1[i]); sum += s1[i]; }
;   l += sum;
; DI void attn_mla_unit(const Params& p, int b, int h, int qb, char* smem, bool pre, int nh, bool has_next) {
;     ...
;     if (kt + 1 < 32) put_stage(smem + ((kt + 1) & 1) * STG);
;     else if (has_next) put_stage(smem);
;     __syncthreads();
;     if (kt + 2 < 32) get_stage(kt + 2);
;     else if (kt == 30 && has_next) { gk += (nh - h) * 64; gv += (nh - h) * 64; get_stage(0); }
;   }
.LBB0_1495:
	v_add_f32_e32 v48, v49, v48
	v_add_f32_e32 v48, v50, v48
	v_add_f32_e32 v48, v51, v48
	v_add_f32_e32 v48, v52, v48
	v_add_f32_e32 v48, v53, v48
	v_add_f32_e32 v48, v54, v48
	v_add_f32_e32 v48, v55, v48
	v_add_f32_e32 v48, v56, v48
	v_add_f32_e32 v48, v57, v48
	v_add_f32_e32 v48, v58, v48
	v_add_f32_e32 v48, v59, v48
	v_add_f32_e32 v48, v60, v48
	v_add_f32_e32 v48, v61, v48
	v_add_f32_e32 v48, v62, v48
	v_add_f32_e32 v48, v63, v48
	v_add_f32_e32 v48, v67, v48
	v_add_f32_e32 v48, v69, v48
	v_add_f32_e32 v48, v70, v48
	v_add_f32_e32 v48, v71, v48
	v_add_f32_e32 v36, v36, v48
	v_add_f32_e32 v36, v37, v36
	v_add_f32_e32 v36, v38, v36
	v_add_f32_e32 v36, v39, v36
	v_add_f32_e32 v36, v40, v36
	v_add_f32_e32 v36, v41, v36
	v_add_f32_e32 v36, v42, v36
	v_add_f32_e32 v36, v43, v36
	v_add_f32_e32 v36, v44, v36
	v_add_f32_e32 v36, v45, v36
	v_add_f32_e32 v36, v46, v36
	s_add_u32 s12, s12, 0x20000
	v_add_f32_e32 v36, v47, v36
	s_addc_u32 s13, s13, 0
	s_add_i32 s18, s18, 1
	s_mov_b64 s[16:17], 0x2000
	v_add_f32_e32 v153, v66, v36
	s_cmp_lg_u32 s12, 0x430000
	v_lshl_add_u64 v[64:65], v[64:65], 0, s[16:17]
	s_cbranch_scc0 .LBB0_1497
	v_mov_b64_e32 v[128:129], v[32:33]
	v_mov_b64_e32 v[130:131], v[34:35]
	s_branch .LBB0_1482

; DI void attn_na_unit(const Params& p, int li, int b, int r, int hp, char* smem) {
;     ...
;   constexpr int KR = 272, VR = 320;
;   const int vbase = tr_base(lane, VR);
;   const int qbk = w & 1, hs = w >> 1, head = 2 * hp + hs;
;   const int wq = 32 * qbk + r32;
;   const int qrow = b * S_ + r * 64 + wq;
;   int cs = wq - 8; cs = cs < 0 ? 0 : (cs > 48 ? 48 : cs);
;   int rs = r - 4; rs = rs < 0 ? 0 : (rs > 56 ? 56 : rs);
;   __syncthreads();
;   for (int idx = tid; idx < 2 * 465; idx += 256) {
;     int hsel = idx >= 465 ? 1 : 0; int rem = idx - hsel * 465;
;     tab[idx] = p.ab_rpb[((size_t)(li * 8 + 2 * hp + hsel)) * 465 + rem] * LOG2E;
;   }
;   bf16x8 qf[4];
; #pragma unroll
;   for (int s = 0; s < 4; ++s) qf[s] = *(const bf16x8*)(qna + (size_t)qrow * 512 + head * 64 + s * 16 + hh * 8);
;   f32x16 O0, O1;
; #pragma unroll
;   for (int i = 0; i < 16; ++i) { O0[i] = 0.f; O1[i] = 0.f; }
;   float m = 0.f, l = 0.f;
;   const int krow = tid >> 4, kpart = tid & 15;
;   const u16* gk = kna + (size_t)(b * S_ + rs * 64 + krow) * 512 + hp * 128 + kpart * 8;
;   const u16* gv = vT + (size_t)(b * S_ + rs * 64 + krow) * 512 + hp * 128 + kpart * 8;
;   u32x4 rk[4], rv[4];
; #pragma unroll
;   for (int i = 0; i < 4; ++i) { rk[i] = *(const u32x4*)(gk + (size_t)i * 16 * 512); rv[i] = *(const u32x4*)(gv + (size_t)i * 16 * 512); }
.LBB0_1537:
	v_lshlrev_b32_e32 v126, 6, v39
	v_mul_u32_u24_e32 v39, 0x110, v33
	v_mul_u32_u24_e32 v42, 0x140, v33
	v_add_f32_e32 v33, 0, v50
	v_add_f32_e32 v50, 0, v60
	v_mul_f32_e32 v34, v50, v34
	v_add_f32_e32 v60, v33, v61
	v_cndmask_b32_e64 v128, v60, v33, s[6:7]
	v_xor_b32_e32 v220, 0x80000000, v128
	v_mov_b32_e32 v221, v220
	v_mov_b64_e32 v[222:223], v[220:221]
	v_mov_b64_e32 v[224:225], v[220:221]
	v_mov_b64_e32 v[226:227], v[220:221]
	v_mov_b64_e32 v[228:229], v[220:221]
	v_mov_b64_e32 v[230:231], v[220:221]
	v_mov_b64_e32 v[232:233], v[220:221]
	v_mov_b64_e32 v[234:235], v[220:221]
	v_cndmask_b32_e64 v127, v34, v50, s[6:7]
	s_movk_i32 s6, 0x7c
	v_mad_u32_u24 v34, v38, s6, v41
	v_add_u32_e32 v32, v34, v32
	v_lshlrev_b32_e32 v37, 2, v37
	v_mul_lo_u32 v36, v36, s6
	v_sub_u32_e32 v32, v32, v37
	v_lshlrev_b32_e32 v37, 1, v35
	v_sub_u32_e32 v32, v32, v36
	v_and_b32_e32 v37, 0x80, v37
	v_sub_u32_e32 v32, v32, v37
	v_add_u32_e32 v130, v120, v32
	v_and_b32_e32 v32, 15, v35
	v_and_b32_e32 v33, 3, v121
	v_lshlrev_b32_e32 v32, 4, v32
	v_lshlrev_b64 v[62:63], 9, v[144:145]
	v_lshl_add_u32 v38, v43, 2, v34
	v_lshl_or_b32 v144, v33, 8, v32
	v_sub_u32_e32 v38, v38, v36
	v_lshl_add_u64 v[32:33], v[62:63], 1, v[144:145]
	v_add_u32_e32 v129, v119, v38
	v_lshl_add_u64 v[114:115], s[34:35], 0, v[32:33]
	s_nop 7
	v_readfirstlane_b32 s6, v114
	s_nop 7
	v_subrev_u32_e32 v246, s6, v114
	v_add_u32_e32 v247, 0x4000, v246
	v_add_u32_e32 v248, 0x8000, v246
	v_add_u32_e32 v249, 0xc000, v246
	s_movk_i32 s9, 0xfc9c
	v_add_u32_e32 v144, v40, v39
	v_add_u32_e32 v148, v40, v42
	v_readfirstlane_b32 s100, v182
	s_branch .LBB0_1539

; DI f32x16 mfma32(bf16x8 a, bf16x8 b, f32x16 c) { return __builtin_amdgcn_mfma_f32_32x32x16_bf16(a, b, c, 0, 0, 0); }
; DI void attn_na_unit(const Params& p, int li, int b, int r, int hp, char* smem) {
;     ...
;   for (int kt = 0; kt < 8; ++kt) {
;     __syncthreads();
; #pragma unroll
;     for (int i = 0; i < 4; ++i) {
;       *(u32x4*)(ks + (krow + 16 * i) * KR + kpart * 16) = rk[i];
;       *(u32x4*)(vs + (krow + 16 * i) * VR + kpart * 16) = rv[i];
;     }
;     __syncthreads();
;     if (kt + 1 < 8) {
;       const int k0 = (kt + 1) * 64;
; #pragma unroll
;       for (int i = 0; i < 4; ++i) { rk[i] = *(const u32x4*)(gk + (size_t)(k0 + i * 16) * 512); rv[i] = *(const u32x4*)(gv + (size_t)(k0 + i * 16) * 512); }
;     }
;     f32x16 s0, s1;
; #pragma unroll
;     for (int i = 0; i < 16; ++i) { s0[i] = -m; s1[i] = -m; }
;     {
;       bf16x8 kf[8];
; #pragma unroll
;       for (int s = 0; s < 4; ++s) {
;         kf[2 * s] = *(const bf16x8*)(ks + r32 * KR + (hs * 64 + s * 16 + hh * 8) * 2);
;         kf[2 * s + 1] = *(const bf16x8*)(ks + (32 + r32) * KR + (hs * 64 + s * 16 + hh * 8) * 2);
;       }
;       __builtin_amdgcn_sched_barrier(0); __builtin_amdgcn_s_setprio(1);
; #pragma unroll
;       for (int s = 0; s < 4; ++s) { s0 = mfma32(kf[2 * s], qf[s], s0); s1 = mfma32(kf[2 * s + 1], qf[s], s1); }
;     __builtin_amdgcn_s_setprio(0);
; }
;     const int drow = rs + kt - r + 7;
;     const float* trow = tab + hs * 465 + drow * 31;
; #pragma unroll
;     for (int i = 0; i < 16; ++i) {
;       const int kc0 = (i & 3) + 8 * (i >> 2) + 4 * hh;
;       const int kc1 = kc0 + 32;
;       const bool v0 = (unsigned)(kc0 - cs) < 16u;
;       const bool v1 = (unsigned)(kc1 - cs) < 16u;
;       const int d0 = v0 ? (kc0 - wq + 15) : 0;
;       const int d1 = v1 ? (kc1 - wq + 15) : 0;
;       const float b0 = trow[d0], b1 = trow[d1];
;       s0[i] = v0 ? s0[i] + b0 : -1e30f;
;       s1[i] = v1 ? s1[i] + b1 : -1e30f;
;     }
;     float alpha; bf16x8 pf[4];
;     const bool resc = softmax_tile(s0, s1, m, l, alpha, pf, lane, kt == 0, true);
.LBB0_1539:
	s_cmpk_eq_i32 s9, 0xff84
	s_barrier
	s_waitcnt vmcnt(7)
	ds_write_b128 v144, v[80:83]
	s_waitcnt vmcnt(6)
	ds_write_b128 v148, v[84:87] offset:17408
	s_waitcnt vmcnt(5)
	ds_write_b128 v144, v[88:91] offset:4352
	s_waitcnt vmcnt(4)
	ds_write_b128 v148, v[92:95] offset:22528
	s_waitcnt vmcnt(3)
	ds_write_b128 v144, v[96:99] offset:8704
	s_waitcnt vmcnt(2)
	ds_write_b128 v148, v[100:103] offset:27648
	s_waitcnt vmcnt(1)
	ds_write_b128 v144, v[104:107] offset:13056
	s_waitcnt vmcnt(0)
	ds_write_b128 v148, v[108:111] offset:32768
	s_waitcnt lgkmcnt(0)
	s_barrier
	s_cbranch_scc1 .LBB0_1541
	v_readfirstlane_b32 s6, v114
	v_readfirstlane_b32 s7, v115
	s_nop 3
	s_add_u32 vcc_lo, s6, 0xfdff4000
	s_addc_u32 vcc_hi, s7, -1
	s_add_u32 s6, s6, 0xffff4000
	s_addc_u32 s7, s7, -1
	global_load_dwordx4 v[80:83], v246, vcc
	global_load_dwordx4 v[84:87], v246, s[6:7]
	global_load_dwordx4 v[88:91], v247, vcc
	global_load_dwordx4 v[92:95], v247, s[6:7]
	global_load_dwordx4 v[96:99], v248, vcc
	global_load_dwordx4 v[100:103], v248, s[6:7]
	global_load_dwordx4 v[104:107], v249, vcc
	global_load_dwordx4 v[108:111], v249, s[6:7]
.LBB0_1541:
	ds_read_b128 v[150:153], v123
	ds_read_b128 v[154:157], v123 offset:32
	ds_read_b128 v[158:161], v123 offset:8704
	ds_read_b128 v[162:165], v123 offset:8736
	ds_read_b128 v[166:169], v123 offset:64
	ds_read_b128 v[170:173], v123 offset:96
	ds_read_b128 v[174:177], v123 offset:8768
	ds_read_b128 v[178:181], v123 offset:8800
	s_setprio 1
	s_waitcnt lgkmcnt(7)
	v_mfma_f32_32x32x16_bf16 v[48:63], v[150:153], v[64:67], v[220:235]
	s_waitcnt lgkmcnt(5)
	v_mfma_f32_32x32x16_bf16 v[32:47], v[158:161], v[64:67], v[220:235]
	v_mfma_f32_32x32x16_bf16 v[48:63], v[154:157], v[68:71], v[48:63]
	s_waitcnt lgkmcnt(4)
	v_mfma_f32_32x32x16_bf16 v[32:47], v[162:165], v[68:71], v[32:47]
	s_waitcnt lgkmcnt(3)
	v_mfma_f32_32x32x16_bf16 v[48:63], v[166:169], v[72:75], v[48:63]
	s_waitcnt lgkmcnt(1)
	v_mfma_f32_32x32x16_bf16 v[32:47], v[174:177], v[72:75], v[32:47]
	v_mfma_f32_32x32x16_bf16 v[48:63], v[170:173], v[76:79], v[48:63]
	s_waitcnt lgkmcnt(0)
	v_mfma_f32_32x32x16_bf16 v[32:47], v[178:181], v[76:79], v[32:47]
	s_setprio 0
	s_bitcmp1_b32 s100, 6
	s_cbranch_scc1 .Lna_el_q1
	v_add_u32_e32 v149, s9, v130
	ds_read_b32 v150, v149 offset:868
	ds_read_b32 v151, v149 offset:872
	ds_read_b32 v152, v149 offset:876
	ds_read_b32 v153, v149 offset:880
	ds_read_b32 v154, v149 offset:900
	ds_read_b32 v155, v149 offset:904
	ds_read_b32 v156, v149 offset:908
	ds_read_b32 v157, v149 offset:912
	ds_read_b32 v158, v149 offset:932
	ds_read_b32 v159, v149 offset:936
	ds_read_b32 v160, v149 offset:940
	ds_read_b32 v161, v149 offset:944
	ds_read_b32 v162, v149 offset:964
	ds_read_b32 v163, v149 offset:968
	ds_read_b32 v164, v149 offset:972
	ds_read_b32 v165, v149 offset:976
	ds_read_b32 v166, v149 offset:996
	ds_read_b32 v167, v149 offset:1000
	ds_read_b32 v168, v149 offset:1004
	ds_read_b32 v169, v149 offset:1008
	s_waitcnt lgkmcnt(0)
	s_nop 7
	v_add_f32_e32 v48, v48, v150
	v_cndmask_b32_e64 v48, v195, v48, s[76:77]
	v_exp_f32_e32 v48, v48
	v_add_f32_e32 v49, v49, v151
	v_cndmask_b32_e64 v49, v195, v49, s[90:91]
	v_exp_f32_e32 v49, v49
	v_add_f32_e32 v50, v50, v152
	v_cndmask_b32_e64 v50, v195, v50, s[96:97]
	v_exp_f32_e32 v50, v50
	v_add_f32_e32 v51, v51, v153
	v_cndmask_b32_e64 v51, v195, v51, s[70:71]
	v_exp_f32_e32 v51, v51
	v_add_f32_e32 v52, v52, v154
	v_cndmask_b32_e64 v52, v195, v52, s[64:65]
	v_exp_f32_e32 v52, v52
	v_add_f32_e32 v53, v53, v155
	v_cndmask_b32_e64 v53, v195, v53, s[66:67]
	v_exp_f32_e32 v53, v53
	v_add_f32_e32 v54, v54, v156
	v_cndmask_b32_e64 v54, v195, v54, s[60:61]
	v_exp_f32_e32 v54, v54
	v_add_f32_e32 v55, v55, v157
	v_cndmask_b32_e64 v55, v195, v55, s[68:69]
	v_exp_f32_e32 v55, v55
	v_add_f32_e32 v56, v56, v158
	v_cndmask_b32_e64 v56, v195, v56, s[52:53]
	v_exp_f32_e32 v56, v56
	v_add_f32_e32 v57, v57, v159
	v_cndmask_b32_e64 v57, v195, v57, s[54:55]
	v_exp_f32_e32 v57, v57
	v_add_f32_e32 v58, v58, v160
	v_cndmask_b32_e64 v58, v195, v58, s[40:41]
	v_exp_f32_e32 v58, v58
	v_add_f32_e32 v59, v59, v161
	v_cndmask_b32_e64 v59, v195, v59, s[42:43]
	v_exp_f32_e32 v59, v59
	v_add_f32_e32 v60, v60, v162
	v_cndmask_b32_e64 v60, v195, v60, s[36:37]
	v_exp_f32_e32 v60, v60
	v_add_f32_e32 v61, v61, v163
	v_cndmask_b32_e64 v61, v195, v61, s[46:47]
	v_exp_f32_e32 v61, v61
	v_add_f32_e32 v62, v62, v164
	v_cndmask_b32_e64 v62, v195, v62, s[86:87]
	v_exp_f32_e32 v62, v62
	v_add_f32_e32 v63, v63, v165
	v_cndmask_b32_e64 v63, v195, v63, s[4:5]
	v_exp_f32_e32 v63, v63
	v_add_f32_e32 v32, v32, v166
	v_cndmask_b32_e64 v32, v195, v32, s[78:79]
	v_exp_f32_e32 v32, v32
	v_add_f32_e32 v33, v33, v167
	v_cndmask_b32_e64 v33, v195, v33, s[92:93]
	v_exp_f32_e32 v33, v33
	v_add_f32_e32 v34, v34, v168
	v_cndmask_b32_e64 v34, v195, v34, s[94:95]
	v_exp_f32_e32 v34, v34
	v_add_f32_e32 v35, v35, v169
	v_cndmask_b32_e64 v35, v195, v35, s[72:73]
	v_exp_f32_e32 v35, v35
	v_add_f32_e32 v149, v48, v49
	v_add_f32_e32 v149, v149, v50
	v_add_f32_e32 v149, v149, v51
	v_add_f32_e32 v149, v149, v52
	v_add_f32_e32 v149, v149, v53
	v_add_f32_e32 v149, v149, v54
	v_add_f32_e32 v149, v149, v55
	v_add_f32_e32 v149, v149, v56
	v_add_f32_e32 v149, v149, v57
	v_add_f32_e32 v149, v149, v58
	v_add_f32_e32 v149, v149, v59
	v_add_f32_e32 v149, v149, v60
	v_add_f32_e32 v149, v149, v61
	v_add_f32_e32 v149, v149, v62
	v_add_f32_e32 v149, v149, v63
	v_add_f32_e32 v149, v149, v32
	v_add_f32_e32 v149, v149, v33
	v_add_f32_e32 v149, v149, v34
	v_add_f32_e32 v149, v149, v35
	v_cvt_pk_bf16_f32 v36, v48, v49
	v_cvt_pk_bf16_f32 v37, v50, v51
	v_cvt_pk_bf16_f32 v38, v52, v53
	v_cvt_pk_bf16_f32 v39, v54, v55
	v_cvt_pk_bf16_f32 v40, v56, v57
	v_cvt_pk_bf16_f32 v41, v58, v59
	v_cvt_pk_bf16_f32 v42, v60, v61
	v_cvt_pk_bf16_f32 v43, v62, v63
	v_cvt_pk_bf16_f32 v44, v32, v33
	v_cvt_pk_bf16_f32 v45, v34, v35
	v_mov_b32_e32 v46, 0
	v_mov_b32_e32 v47, 0
	v_mov_b32_e32 v33, v149
	s_branch .Lna_el_done
; DI bool softmax_tile(f32x16& s0, f32x16& s1, float& m, float& l, float& alpha, bf16x8* pf, int lane, bool first, bool check) {
;     ...
;   float sum = 0.f;
; #pragma unroll
;   for (int i = 0; i < 16; ++i) { s0[i] = __builtin_amdgcn_exp2f(s0[i]); sum += s0[i]; }
; #pragma unroll
;   for (int i = 0; i < 16; ++i) { s1[i] = __builtin_amdgcn_exp2f(s1[i]); sum += s1[i]; }
;   l += sum;
;   pf[0] = pack8(s0, 0); pf[1] = pack8(s0, 8); pf[2] = pack8(s1, 0); pf[3] = pack8(s1, 8);
; DI void attn_na_unit(const Params& p, int li, int b, int r, int hp, char* smem) {
;     ...
;     const int drow = rs + kt - r + 7;
;     const float* trow = tab + hs * 465 + drow * 31;
; #pragma unroll
;     for (int i = 0; i < 16; ++i) {
;       const int kc0 = (i & 3) + 8 * (i >> 2) + 4 * hh;
;       const int kc1 = kc0 + 32;
;       const bool v0 = (unsigned)(kc0 - cs) < 16u;
;       const bool v1 = (unsigned)(kc1 - cs) < 16u;
;       const int d0 = v0 ? (kc0 - wq + 15) : 0;
;       const int d1 = v1 ? (kc1 - wq + 15) : 0;
;       const float b0 = trow[d0], b1 = trow[d1];
;       s0[i] = v0 ? s0[i] + b0 : -1e30f;
;       s1[i] = v1 ? s1[i] + b1 : -1e30f;
;     }
;     float alpha; bf16x8 pf[4];
;     const bool resc = softmax_tile(s0, s1, m, l, alpha, pf, lane, kt == 0, true);
.Lna_el_q1:
	v_add_u32_e32 v149, s9, v130
	ds_read_b32 v150, v149 offset:964
	ds_read_b32 v151, v149 offset:968
	ds_read_b32 v152, v149 offset:972
	ds_read_b32 v153, v149 offset:976
	ds_read_b32 v154, v149 offset:996
	ds_read_b32 v155, v149 offset:1000
	ds_read_b32 v156, v149 offset:1004
	ds_read_b32 v157, v149 offset:1008
	ds_read_b32 v158, v149 offset:1028
	ds_read_b32 v159, v149 offset:1032
	ds_read_b32 v160, v149 offset:1036
	ds_read_b32 v161, v149 offset:1040
	ds_read_b32 v162, v149 offset:1060
	ds_read_b32 v163, v149 offset:1064
	ds_read_b32 v164, v149 offset:1068
	ds_read_b32 v165, v149 offset:1072
	ds_read_b32 v166, v149 offset:1092
	ds_read_b32 v167, v149 offset:1096
	ds_read_b32 v168, v149 offset:1100
	ds_read_b32 v169, v149 offset:1104
	s_waitcnt lgkmcnt(0)
	s_nop 7
	v_add_f32_e32 v60, v60, v150
	v_cndmask_b32_e64 v60, v195, v60, s[36:37]
	v_exp_f32_e32 v60, v60
	v_add_f32_e32 v61, v61, v151
	v_cndmask_b32_e64 v61, v195, v61, s[46:47]
	v_exp_f32_e32 v61, v61
	v_add_f32_e32 v62, v62, v152
	v_cndmask_b32_e64 v62, v195, v62, s[86:87]
	v_exp_f32_e32 v62, v62
	v_add_f32_e32 v63, v63, v153
	v_cndmask_b32_e64 v63, v195, v63, s[4:5]
	v_exp_f32_e32 v63, v63
	v_add_f32_e32 v32, v32, v154
	v_cndmask_b32_e64 v32, v195, v32, s[78:79]
	v_exp_f32_e32 v32, v32
	v_add_f32_e32 v33, v33, v155
	v_cndmask_b32_e64 v33, v195, v33, s[92:93]
	v_exp_f32_e32 v33, v33
	v_add_f32_e32 v34, v34, v156
	v_cndmask_b32_e64 v34, v195, v34, s[94:95]
	v_exp_f32_e32 v34, v34
	v_add_f32_e32 v35, v35, v157
	v_cndmask_b32_e64 v35, v195, v35, s[72:73]
	v_exp_f32_e32 v35, v35
	v_add_f32_e32 v36, v36, v158
	v_cndmask_b32_e64 v36, v195, v36, s[80:81]
	v_exp_f32_e32 v36, v36
	v_add_f32_e32 v37, v37, v159
	v_cndmask_b32_e64 v37, v195, v37, s[74:75]
	v_exp_f32_e32 v37, v37
	v_add_f32_e32 v38, v38, v160
	v_cndmask_b32_e64 v38, v195, v38, s[58:59]
	v_exp_f32_e32 v38, v38
	v_add_f32_e32 v39, v39, v161
	v_cndmask_b32_e64 v39, v195, v39, s[48:49]
	v_exp_f32_e32 v39, v39
	v_add_f32_e32 v40, v40, v162
	v_cndmask_b32_e64 v40, v195, v40, s[50:51]
	v_exp_f32_e32 v40, v40
	v_add_f32_e32 v41, v41, v163
	v_cndmask_b32_e64 v41, v195, v41, s[62:63]
	v_exp_f32_e32 v41, v41
	v_add_f32_e32 v42, v42, v164
	v_cndmask_b32_e64 v42, v195, v42, s[38:39]
	v_exp_f32_e32 v42, v42
	v_add_f32_e32 v43, v43, v165
	v_cndmask_b32_e64 v43, v195, v43, s[44:45]
	v_exp_f32_e32 v43, v43
	v_add_f32_e32 v44, v44, v166
	v_cndmask_b32_e64 v44, v195, v44, s[56:57]
	v_exp_f32_e32 v44, v44
	v_add_f32_e32 v45, v45, v167
	v_cndmask_b32_e64 v45, v195, v45, s[82:83]
	v_exp_f32_e32 v45, v45
	v_add_f32_e32 v46, v46, v168
	v_cndmask_b32_e64 v46, v195, v46, s[84:85]
	v_exp_f32_e32 v46, v46
	v_add_f32_e32 v47, v47, v169
	v_cndmask_b32_e64 v47, v195, v47, s[2:3]
	v_exp_f32_e32 v47, v47
	v_add_f32_e32 v149, v60, v61
	v_add_f32_e32 v149, v149, v62
	v_add_f32_e32 v149, v149, v63
	v_add_f32_e32 v149, v149, v32
	v_add_f32_e32 v149, v149, v33
	v_add_f32_e32 v149, v149, v34
	v_add_f32_e32 v149, v149, v35
	v_add_f32_e32 v149, v149, v36
	v_add_f32_e32 v149, v149, v37
	v_add_f32_e32 v149, v149, v38
	v_add_f32_e32 v149, v149, v39
	v_add_f32_e32 v149, v149, v40
	v_add_f32_e32 v149, v149, v41
	v_add_f32_e32 v149, v149, v42
	v_add_f32_e32 v149, v149, v43
	v_add_f32_e32 v149, v149, v44
	v_add_f32_e32 v149, v149, v45
	v_add_f32_e32 v149, v149, v46
	v_add_f32_e32 v149, v149, v47
	v_cvt_pk_bf16_f32 v48, v40, v41
	v_cvt_pk_bf16_f32 v49, v42, v43
	v_cvt_pk_bf16_f32 v50, v44, v45
	v_cvt_pk_bf16_f32 v51, v46, v47
	v_cvt_pk_bf16_f32 v44, v32, v33
	v_cvt_pk_bf16_f32 v45, v34, v35
	v_cvt_pk_bf16_f32 v46, v36, v37
	v_cvt_pk_bf16_f32 v47, v38, v39
	v_cvt_pk_bf16_f32 v42, v60, v61
	v_cvt_pk_bf16_f32 v43, v62, v63
	v_mov_b32_e32 v40, 0
	v_mov_b32_e32 v41, 0
	v_mov_b32_e32 v33, v149
